# grid barrier: flat release (non-leader WGs poll cross-XCD generation directly, drop per-XCD release hop)
# speedup vs baseline: 1.0437x; 1.0025x over previous
; __device__ __forceinline__ unsigned xb_ld(unsigned* p)              { return __hip_atomic_load(p, __ATOMIC_RELAXED, __HIP_MEMORY_SCOPE_AGENT); }
; __device__ __forceinline__ unsigned xb_add(unsigned* p, unsigned v) { return __hip_atomic_fetch_add(p, v, __ATOMIC_RELAXED, __HIP_MEMORY_SCOPE_AGENT); }
; #define XB_SPIN(cond, bar) do { unsigned _sp = 0; while (cond) { __builtin_amdgcn_s_sleep(1); \
;     if ((++_sp & 255u) == 0u) { if (xb_ld(&(bar)[XB_TMO])) break; if (_sp > XB_SPIN_CAP) { atomicAdd(&(bar)[XB_TMO], 1u); break; } } } } while (0)
; __device__ __forceinline__ void xcd_barrier(const XcdBarrier& b) {
;     ...
;         const unsigned old = xb_add(&bar[XB_XSUB(b.x)], 1u);
;         const unsigned gen = old / nloc;
;         if (old + 1u == (gen + 1u) * nloc) {
;             __builtin_amdgcn_fence(__ATOMIC_RELEASE, "agent");
;             asm volatile("s_waitcnt vmcnt(0)" ::: "memory");
;             const unsigned og = xb_add(&bar[XB_TOP], 1u);
;             const unsigned tg = og / nx;
;             if (og + 1u == (tg + 1u) * nx) xb_add(&bar[XB_TOPGEN], 1u);
;             else XB_SPIN(xb_ld(&bar[XB_TOPGEN]) == tg, bar);
;             __builtin_amdgcn_fence(__ATOMIC_ACQUIRE, "agent");
;             xb_add(&bar[XB_XGEN(b.x)], 1u);
;             asm volatile("s_waitcnt vmcnt(0)" ::: "memory");
;         } else {
;             XB_SPIN(xb_ld(&bar[XB_XGEN(b.x)]) == gen, bar);
;             __builtin_amdgcn_fence(__ATOMIC_ACQUIRE, "agent");
;             asm volatile("s_waitcnt vmcnt(0)" ::: "memory");
;         }
.LBB0_122:
	s_or_b64 exec, exec, s[10:11]
	v_cvt_f32_u32_e32 v4, v2
	s_waitcnt vmcnt(0)
	v_readfirstlane_b32 s8, v3
	v_sub_u32_e32 v3, 0, v2
	v_rcp_iflag_f32_e32 v4, v4
	v_add_u32_e32 v5, s8, v1
	v_mul_f32_e32 v4, 0x4f7ffffe, v4
	v_cvt_u32_f32_e32 v4, v4
	v_mul_lo_u32 v1, v3, v4
	v_mul_hi_u32 v1, v4, v1
	v_add_u32_e32 v1, v4, v1
	v_mul_hi_u32 v1, v5, v1
	v_mul_lo_u32 v3, v1, v2
	v_sub_u32_e32 v3, v5, v3
	v_add_u32_e32 v4, 1, v1
	v_cmp_ge_u32_e32 vcc, v3, v2
	s_nop 1
	v_cndmask_b32_e32 v1, v1, v4, vcc
	v_sub_u32_e32 v4, v3, v2
	v_cndmask_b32_e32 v3, v3, v4, vcc
	v_add_u32_e32 v4, 1, v1
	v_cmp_ge_u32_e32 vcc, v3, v2
	v_add_u32_e32 v3, 1, v5
	s_nop 0
	v_cndmask_b32_e32 v1, v1, v4, vcc
	v_mul_lo_u32 v4, v2, v1
	v_add_u32_e32 v2, v4, v2
	v_cmp_ne_u32_e32 vcc, v3, v2
	s_and_saveexec_b64 s[8:9], vcc
	s_xor_b64 s[8:9], exec, s[8:9]
	s_cbranch_execz .LBB0_136
	s_waitcnt lgkmcnt(0)
	v_mov_b32_e32 v0, 0
	s_add_u32 s14, s58, 0x903500
	s_addc_u32 s15, s59, 0
	global_load_dword v0, v0, s[14:15] sc1
	s_waitcnt vmcnt(0)
	v_cmp_eq_u32_e32 vcc, v0, v1
	s_and_saveexec_b64 s[10:11], vcc
	s_cbranch_execz .LBB0_135
	s_add_u32 s12, s58, 0x900200
	s_addc_u32 s13, s59, 0
	s_mov_b32 s36, 1
	s_mov_b64 s[16:17], 0
	v_mov_b32_e32 v0, 0
	s_branch .LBB0_126

; __device__ __forceinline__ unsigned xb_add(unsigned* p, unsigned v) { return __hip_atomic_fetch_add(p, v, __ATOMIC_RELAXED, __HIP_MEMORY_SCOPE_AGENT); }
; __device__ __forceinline__ void xcd_barrier(const XcdBarrier& b) {
;     ...
;             __builtin_amdgcn_fence(__ATOMIC_ACQUIRE, "agent");
;             xb_add(&bar[XB_XGEN(b.x)], 1u);
.LBB0_153:
	s_or_b64 exec, exec, s[8:9]
	s_mov_b64 s[8:9], exec
	v_mbcnt_lo_u32_b32 v0, s8, 0
	v_mbcnt_hi_u32_b32 v0, s9, v0
	v_cmp_eq_u32_e32 vcc, 0, v0
	s_waitcnt vmcnt(0)
	buffer_inv sc1
	s_and_saveexec_b64 s[10:11], vcc
	s_cbranch_execz .LBB0_155
	s_bcnt1_i32_b64 s8, s[8:9]
	v_mov_b32_e32 v0, 0x2000
	v_mov_b32_e32 v1, s8
.LBB0_155:
	s_or_b64 exec, exec, s[10:11]
	s_waitcnt vmcnt(0)

; __device__ __forceinline__ unsigned xb_ld(unsigned* p)              { return __hip_atomic_load(p, __ATOMIC_RELAXED, __HIP_MEMORY_SCOPE_AGENT); }
; __device__ __forceinline__ unsigned xb_add(unsigned* p, unsigned v) { return __hip_atomic_fetch_add(p, v, __ATOMIC_RELAXED, __HIP_MEMORY_SCOPE_AGENT); }
; #define XB_SPIN(cond, bar) do { unsigned _sp = 0; while (cond) { __builtin_amdgcn_s_sleep(1); \
;     if ((++_sp & 255u) == 0u) { if (xb_ld(&(bar)[XB_TMO])) break; if (_sp > XB_SPIN_CAP) { atomicAdd(&(bar)[XB_TMO], 1u); break; } } } } while (0)
; __device__ __forceinline__ void xcd_barrier(const XcdBarrier& b) {
;     ...
;         const unsigned old = xb_add(&bar[XB_XSUB(b.x)], 1u);
;         const unsigned gen = old / nloc;
;         if (old + 1u == (gen + 1u) * nloc) {
;             __builtin_amdgcn_fence(__ATOMIC_RELEASE, "agent");
;             asm volatile("s_waitcnt vmcnt(0)" ::: "memory");
;             const unsigned og = xb_add(&bar[XB_TOP], 1u);
;             const unsigned tg = og / nx;
;             if (og + 1u == (tg + 1u) * nx) xb_add(&bar[XB_TOPGEN], 1u);
;             else XB_SPIN(xb_ld(&bar[XB_TOPGEN]) == tg, bar);
;             __builtin_amdgcn_fence(__ATOMIC_ACQUIRE, "agent");
;             xb_add(&bar[XB_XGEN(b.x)], 1u);
;             asm volatile("s_waitcnt vmcnt(0)" ::: "memory");
;         } else {
;             XB_SPIN(xb_ld(&bar[XB_XGEN(b.x)]) == gen, bar);
.LBB0_187:
	s_or_b64 exec, exec, s[22:23]
	v_cvt_f32_u32_e32 v4, v2
	s_waitcnt vmcnt(0)
	v_readfirstlane_b32 s3, v3
	v_sub_u32_e32 v3, 0, v2
	v_rcp_iflag_f32_e32 v4, v4
	v_add_u32_e32 v5, s3, v1
	v_mul_f32_e32 v4, 0x4f7ffffe, v4
	v_cvt_u32_f32_e32 v4, v4
	v_mul_lo_u32 v1, v3, v4
	v_mul_hi_u32 v1, v4, v1
	v_add_u32_e32 v1, v4, v1
	v_mul_hi_u32 v1, v5, v1
	v_mul_lo_u32 v3, v1, v2
	v_sub_u32_e32 v3, v5, v3
	v_add_u32_e32 v4, 1, v1
	v_cmp_ge_u32_e32 vcc, v3, v2
	s_nop 1
	v_cndmask_b32_e32 v1, v1, v4, vcc
	v_sub_u32_e32 v4, v3, v2
	v_cndmask_b32_e32 v3, v3, v4, vcc
	v_add_u32_e32 v4, 1, v1
	v_cmp_ge_u32_e32 vcc, v3, v2
	v_add_u32_e32 v3, 1, v5
	s_nop 0
	v_cndmask_b32_e32 v1, v1, v4, vcc
	v_mul_lo_u32 v4, v2, v1
	v_add_u32_e32 v2, v4, v2
	v_cmp_ne_u32_e32 vcc, v3, v2
	s_and_saveexec_b64 s[22:23], vcc
	s_xor_b64 s[22:23], exec, s[22:23]
	s_cbranch_execz .LBB0_201
	v_readlane_b32 s4, v240, 6
	s_waitcnt lgkmcnt(0)
	v_mov_b32_e32 v0, 0
	v_readlane_b32 s5, v240, 7
	s_nop 4
	global_load_dword v2, v0, s[4:5] sc1
	s_waitcnt vmcnt(0)
	v_cmp_eq_u32_e32 vcc, v2, v1
	s_and_saveexec_b64 s[24:25], vcc
	s_cbranch_execz .LBB0_200
	s_mov_b32 s3, 1
	s_mov_b64 s[26:27], 0
	s_branch .LBB0_191

; __device__ __forceinline__ unsigned xb_ld(unsigned* p)              { return __hip_atomic_load(p, __ATOMIC_RELAXED, __HIP_MEMORY_SCOPE_AGENT); }
; #define XB_SPIN(cond, bar) do { unsigned _sp = 0; while (cond) { __builtin_amdgcn_s_sleep(1); \
;     if ((++_sp & 255u) == 0u) { if (xb_ld(&(bar)[XB_TMO])) break; if (_sp > XB_SPIN_CAP) { atomicAdd(&(bar)[XB_TMO], 1u); break; } } } } while (0)
; __device__ __forceinline__ void xcd_barrier(const XcdBarrier& b) {
;     ...
;         } else {
;             XB_SPIN(xb_ld(&bar[XB_XGEN(b.x)]) == gen, bar);
;             __builtin_amdgcn_fence(__ATOMIC_ACQUIRE, "agent");
;             asm volatile("s_waitcnt vmcnt(0)" ::: "memory");
.LBB0_195:
	v_readlane_b32 s4, v240, 6
	v_readlane_b32 s5, v240, 7
	s_add_i32 s3, s3, 1
	s_mov_b64 s[40:41], -1
	s_nop 2
	global_load_dword v2, v0, s[4:5] sc1
	s_waitcnt vmcnt(0)
	v_cmp_ne_u32_e32 vcc, v2, v1
	s_orn2_b64 s[38:39], vcc, exec
	s_branch .LBB0_190

; __device__ __forceinline__ unsigned xb_add(unsigned* p, unsigned v) { return __hip_atomic_fetch_add(p, v, __ATOMIC_RELAXED, __HIP_MEMORY_SCOPE_AGENT); }
; __device__ __forceinline__ void xcd_barrier(const XcdBarrier& b) {
;     ...
;             __builtin_amdgcn_fence(__ATOMIC_ACQUIRE, "agent");
;             xb_add(&bar[XB_XGEN(b.x)], 1u);
.LBB0_218:
	s_or_b64 exec, exec, s[22:23]
	s_mov_b64 s[22:23], exec
	v_mbcnt_lo_u32_b32 v0, s22, 0
	v_mbcnt_hi_u32_b32 v0, s23, v0
	v_cmp_eq_u32_e32 vcc, 0, v0
	s_waitcnt vmcnt(0)
	buffer_inv sc1
	s_and_saveexec_b64 s[24:25], vcc
	s_cbranch_execz .LBB0_220
	s_bcnt1_i32_b64 s3, s[22:23]
	v_readlane_b32 s4, v240, 2
	v_mov_b32_e32 v0, 0
	v_mov_b32_e32 v1, s3
	v_readlane_b32 s5, v240, 3
	s_nop 4
.LBB0_220:
	s_or_b64 exec, exec, s[24:25]
	s_waitcnt vmcnt(0)

; __device__ __forceinline__ unsigned xb_add(unsigned* p, unsigned v) { return __hip_atomic_fetch_add(p, v, __ATOMIC_RELAXED, __HIP_MEMORY_SCOPE_AGENT); }
; __device__ __forceinline__ void xcd_barrier(const XcdBarrier& b) {
;     ...
;             __builtin_amdgcn_fence(__ATOMIC_ACQUIRE, "agent");
;             xb_add(&bar[XB_XGEN(b.x)], 1u);
.LBB0_294:
	s_or_b64 exec, exec, s[22:23]
	s_mov_b64 s[22:23], exec
	v_mbcnt_lo_u32_b32 v0, s22, 0
	v_mbcnt_hi_u32_b32 v0, s23, v0
	v_cmp_eq_u32_e32 vcc, 0, v0
	s_waitcnt vmcnt(0)
	buffer_inv sc1
	s_and_saveexec_b64 s[24:25], vcc
	s_cbranch_execz .LBB0_296
	s_bcnt1_i32_b64 s3, s[22:23]
	v_readlane_b32 s4, v240, 2
	v_mov_b32_e32 v0, 0
	v_mov_b32_e32 v1, s3
	v_readlane_b32 s5, v240, 3
	s_nop 4
.LBB0_296:
	s_or_b64 exec, exec, s[24:25]
	s_waitcnt vmcnt(0)

; __device__ __forceinline__ unsigned xb_add(unsigned* p, unsigned v) { return __hip_atomic_fetch_add(p, v, __ATOMIC_RELAXED, __HIP_MEMORY_SCOPE_AGENT); }
; __device__ __forceinline__ void xcd_barrier(const XcdBarrier& b) {
;     ...
;             __builtin_amdgcn_fence(__ATOMIC_ACQUIRE, "agent");
;             xb_add(&bar[XB_XGEN(b.x)], 1u);
.LBB0_351:
	s_or_b64 exec, exec, s[22:23]
	s_mov_b64 s[22:23], exec
	v_mbcnt_lo_u32_b32 v0, s22, 0
	v_mbcnt_hi_u32_b32 v0, s23, v0
	v_cmp_eq_u32_e32 vcc, 0, v0
	s_waitcnt vmcnt(0)
	buffer_inv sc1
	s_and_saveexec_b64 s[24:25], vcc
	s_cbranch_execz .LBB0_353
	s_bcnt1_i32_b64 s3, s[22:23]
	v_readlane_b32 s4, v240, 2
	v_mov_b32_e32 v0, 0
	v_mov_b32_e32 v1, s3
	v_readlane_b32 s5, v240, 3
	s_nop 4
.LBB0_353:
	s_or_b64 exec, exec, s[24:25]
	s_waitcnt vmcnt(0)

; __device__ __forceinline__ unsigned xb_ld(unsigned* p)              { return __hip_atomic_load(p, __ATOMIC_RELAXED, __HIP_MEMORY_SCOPE_AGENT); }
; __device__ __forceinline__ unsigned xb_add(unsigned* p, unsigned v) { return __hip_atomic_fetch_add(p, v, __ATOMIC_RELAXED, __HIP_MEMORY_SCOPE_AGENT); }
; #define XB_SPIN(cond, bar) do { unsigned _sp = 0; while (cond) { __builtin_amdgcn_s_sleep(1); \
;     if ((++_sp & 255u) == 0u) { if (xb_ld(&(bar)[XB_TMO])) break; if (_sp > XB_SPIN_CAP) { atomicAdd(&(bar)[XB_TMO], 1u); break; } } } } while (0)
; __device__ __forceinline__ void xcd_barrier(const XcdBarrier& b) {
;     ...
;         const unsigned old = xb_add(&bar[XB_XSUB(b.x)], 1u);
;         const unsigned gen = old / nloc;
;         if (old + 1u == (gen + 1u) * nloc) {
;             __builtin_amdgcn_fence(__ATOMIC_RELEASE, "agent");
;             asm volatile("s_waitcnt vmcnt(0)" ::: "memory");
;             const unsigned og = xb_add(&bar[XB_TOP], 1u);
;             const unsigned tg = og / nx;
;             if (og + 1u == (tg + 1u) * nx) xb_add(&bar[XB_TOPGEN], 1u);
;             else XB_SPIN(xb_ld(&bar[XB_TOPGEN]) == tg, bar);
;             __builtin_amdgcn_fence(__ATOMIC_ACQUIRE, "agent");
;             xb_add(&bar[XB_XGEN(b.x)], 1u);
;             asm volatile("s_waitcnt vmcnt(0)" ::: "memory");
;         } else {
;             XB_SPIN(xb_ld(&bar[XB_XGEN(b.x)]) == gen, bar);
.LBB0_448:
	s_or_b64 exec, exec, s[22:23]
	v_cvt_f32_u32_e32 v4, v2
	s_waitcnt vmcnt(0)
	v_readfirstlane_b32 s3, v3
	v_sub_u32_e32 v3, 0, v2
	v_rcp_iflag_f32_e32 v4, v4
	v_add_u32_e32 v5, s3, v1
	v_mul_f32_e32 v4, 0x4f7ffffe, v4
	v_cvt_u32_f32_e32 v4, v4
	v_mul_lo_u32 v1, v3, v4
	v_mul_hi_u32 v1, v4, v1
	v_add_u32_e32 v1, v4, v1
	v_mul_hi_u32 v1, v5, v1
	v_mul_lo_u32 v3, v1, v2
	v_sub_u32_e32 v3, v5, v3
	v_add_u32_e32 v4, 1, v1
	v_cmp_ge_u32_e32 vcc, v3, v2
	s_nop 1
	v_cndmask_b32_e32 v1, v1, v4, vcc
	v_sub_u32_e32 v4, v3, v2
	v_cndmask_b32_e32 v3, v3, v4, vcc
	v_add_u32_e32 v4, 1, v1
	v_cmp_ge_u32_e32 vcc, v3, v2
	v_add_u32_e32 v3, 1, v5
	s_nop 0
	v_cndmask_b32_e32 v1, v1, v4, vcc
	v_mul_lo_u32 v4, v2, v1
	v_add_u32_e32 v2, v4, v2
	v_cmp_ne_u32_e32 vcc, v3, v2
	s_and_saveexec_b64 s[22:23], vcc
	s_xor_b64 s[22:23], exec, s[22:23]
	s_cbranch_execz .LBB0_462
	v_readlane_b32 s4, v240, 6
	s_waitcnt lgkmcnt(0)
	v_mov_b32_e32 v0, 0
	v_readlane_b32 s5, v240, 7
	s_nop 4
	global_load_dword v2, v0, s[4:5] sc1
	s_waitcnt vmcnt(0)
	v_cmp_eq_u32_e32 vcc, v2, v1
	s_and_saveexec_b64 s[26:27], vcc
	s_cbranch_execz .LBB0_461
	s_mov_b32 s3, 1
	s_mov_b64 s[36:37], 0
	s_branch .LBB0_452

; __device__ __forceinline__ unsigned xb_ld(unsigned* p)              { return __hip_atomic_load(p, __ATOMIC_RELAXED, __HIP_MEMORY_SCOPE_AGENT); }
; #define XB_SPIN(cond, bar) do { unsigned _sp = 0; while (cond) { __builtin_amdgcn_s_sleep(1); \
;     if ((++_sp & 255u) == 0u) { if (xb_ld(&(bar)[XB_TMO])) break; if (_sp > XB_SPIN_CAP) { atomicAdd(&(bar)[XB_TMO], 1u); break; } } } } while (0)
; __device__ __forceinline__ void xcd_barrier(const XcdBarrier& b) {
;     ...
;         } else {
;             XB_SPIN(xb_ld(&bar[XB_XGEN(b.x)]) == gen, bar);
;             __builtin_amdgcn_fence(__ATOMIC_ACQUIRE, "agent");
;             asm volatile("s_waitcnt vmcnt(0)" ::: "memory");
.LBB0_456:
	v_readlane_b32 s4, v240, 6
	v_readlane_b32 s5, v240, 7
	s_add_i32 s3, s3, 1
	s_mov_b64 s[44:45], -1
	s_nop 2
	global_load_dword v2, v0, s[4:5] sc1
	s_waitcnt vmcnt(0)
	v_cmp_ne_u32_e32 vcc, v2, v1
	s_orn2_b64 s[40:41], vcc, exec
	s_branch .LBB0_451

; __device__ __forceinline__ unsigned xb_add(unsigned* p, unsigned v) { return __hip_atomic_fetch_add(p, v, __ATOMIC_RELAXED, __HIP_MEMORY_SCOPE_AGENT); }
; __device__ __forceinline__ void xcd_barrier(const XcdBarrier& b) {
;     ...
;             __builtin_amdgcn_fence(__ATOMIC_ACQUIRE, "agent");
;             xb_add(&bar[XB_XGEN(b.x)], 1u);
.LBB0_479:
	s_or_b64 exec, exec, s[22:23]
	s_mov_b64 s[22:23], exec
	v_mbcnt_lo_u32_b32 v0, s22, 0
	v_mbcnt_hi_u32_b32 v0, s23, v0
	v_cmp_eq_u32_e32 vcc, 0, v0
	s_waitcnt vmcnt(0)
	buffer_inv sc1
	s_and_saveexec_b64 s[26:27], vcc
	s_cbranch_execz .LBB0_481
	s_bcnt1_i32_b64 s3, s[22:23]
	v_readlane_b32 s4, v240, 2
	v_mov_b32_e32 v0, 0
	v_mov_b32_e32 v1, s3
	v_readlane_b32 s5, v240, 3
	s_nop 4
.LBB0_481:
	s_or_b64 exec, exec, s[26:27]
	s_waitcnt vmcnt(0)

; __device__ __forceinline__ unsigned xb_add(unsigned* p, unsigned v) { return __hip_atomic_fetch_add(p, v, __ATOMIC_RELAXED, __HIP_MEMORY_SCOPE_AGENT); }
; __device__ __forceinline__ void xcd_barrier(const XcdBarrier& b) {
;     ...
;             __builtin_amdgcn_fence(__ATOMIC_ACQUIRE, "agent");
;             xb_add(&bar[XB_XGEN(b.x)], 1u);
.LBB0_536:
	s_or_b64 exec, exec, s[26:27]
	s_mov_b64 s[26:27], exec
	v_mbcnt_lo_u32_b32 v0, s26, 0
	v_mbcnt_hi_u32_b32 v0, s27, v0
	v_cmp_eq_u32_e32 vcc, 0, v0
	s_waitcnt vmcnt(0)
	buffer_inv sc1
	s_and_saveexec_b64 s[36:37], vcc
	s_cbranch_execz .LBB0_538
	s_bcnt1_i32_b64 s3, s[26:27]
	v_readlane_b32 s4, v240, 2
	v_mov_b32_e32 v0, 0
	v_mov_b32_e32 v1, s3
	v_readlane_b32 s5, v240, 3
	s_nop 4
.LBB0_538:
	s_or_b64 exec, exec, s[36:37]
	s_waitcnt vmcnt(0)

; __device__ __forceinline__ unsigned xb_ld(unsigned* p)              { return __hip_atomic_load(p, __ATOMIC_RELAXED, __HIP_MEMORY_SCOPE_AGENT); }
; __device__ __forceinline__ unsigned xb_add(unsigned* p, unsigned v) { return __hip_atomic_fetch_add(p, v, __ATOMIC_RELAXED, __HIP_MEMORY_SCOPE_AGENT); }
; #define XB_SPIN(cond, bar) do { unsigned _sp = 0; while (cond) { __builtin_amdgcn_s_sleep(1); \
;     if ((++_sp & 255u) == 0u) { if (xb_ld(&(bar)[XB_TMO])) break; if (_sp > XB_SPIN_CAP) { atomicAdd(&(bar)[XB_TMO], 1u); break; } } } } while (0)
; __device__ __forceinline__ void xcd_barrier(const XcdBarrier& b) {
;     ...
;         const unsigned old = xb_add(&bar[XB_XSUB(b.x)], 1u);
;         const unsigned gen = old / nloc;
;         if (old + 1u == (gen + 1u) * nloc) {
;             __builtin_amdgcn_fence(__ATOMIC_RELEASE, "agent");
;             asm volatile("s_waitcnt vmcnt(0)" ::: "memory");
;             const unsigned og = xb_add(&bar[XB_TOP], 1u);
;             const unsigned tg = og / nx;
;             if (og + 1u == (tg + 1u) * nx) xb_add(&bar[XB_TOPGEN], 1u);
;             else XB_SPIN(xb_ld(&bar[XB_TOPGEN]) == tg, bar);
;             __builtin_amdgcn_fence(__ATOMIC_ACQUIRE, "agent");
;             xb_add(&bar[XB_XGEN(b.x)], 1u);
;             asm volatile("s_waitcnt vmcnt(0)" ::: "memory");
;         } else {
;             XB_SPIN(xb_ld(&bar[XB_XGEN(b.x)]) == gen, bar);
.LBB0_681:
	s_or_b64 exec, exec, s[22:23]
	v_cvt_f32_u32_e32 v4, v2
	s_waitcnt vmcnt(0)
	v_readfirstlane_b32 s3, v3
	v_sub_u32_e32 v3, 0, v2
	v_rcp_iflag_f32_e32 v4, v4
	v_add_u32_e32 v5, s3, v1
	v_mul_f32_e32 v4, 0x4f7ffffe, v4
	v_cvt_u32_f32_e32 v4, v4
	v_mul_lo_u32 v1, v3, v4
	v_mul_hi_u32 v1, v4, v1
	v_add_u32_e32 v1, v4, v1
	v_mul_hi_u32 v1, v5, v1
	v_mul_lo_u32 v3, v1, v2
	v_sub_u32_e32 v3, v5, v3
	v_add_u32_e32 v4, 1, v1
	v_cmp_ge_u32_e32 vcc, v3, v2
	s_nop 1
	v_cndmask_b32_e32 v1, v1, v4, vcc
	v_sub_u32_e32 v4, v3, v2
	v_cndmask_b32_e32 v3, v3, v4, vcc
	v_add_u32_e32 v4, 1, v1
	v_cmp_ge_u32_e32 vcc, v3, v2
	v_add_u32_e32 v3, 1, v5
	s_nop 0
	v_cndmask_b32_e32 v1, v1, v4, vcc
	v_mul_lo_u32 v4, v2, v1
	v_add_u32_e32 v2, v4, v2
	v_cmp_ne_u32_e32 vcc, v3, v2
	s_and_saveexec_b64 s[22:23], vcc
	s_xor_b64 s[22:23], exec, s[22:23]
	s_cbranch_execz .LBB0_695
	v_readlane_b32 s4, v240, 6
	s_waitcnt lgkmcnt(0)
	v_mov_b32_e32 v0, 0
	v_readlane_b32 s5, v240, 7
	s_nop 4
	global_load_dword v2, v0, s[4:5] sc1
	s_waitcnt vmcnt(0)
	v_cmp_eq_u32_e32 vcc, v2, v1
	s_and_saveexec_b64 s[26:27], vcc
	s_cbranch_execz .LBB0_694
	s_mov_b32 s3, 1
	s_mov_b64 s[28:29], 0
	s_branch .LBB0_685

; __device__ __forceinline__ unsigned xb_ld(unsigned* p)              { return __hip_atomic_load(p, __ATOMIC_RELAXED, __HIP_MEMORY_SCOPE_AGENT); }
; #define XB_SPIN(cond, bar) do { unsigned _sp = 0; while (cond) { __builtin_amdgcn_s_sleep(1); \
;     if ((++_sp & 255u) == 0u) { if (xb_ld(&(bar)[XB_TMO])) break; if (_sp > XB_SPIN_CAP) { atomicAdd(&(bar)[XB_TMO], 1u); break; } } } } while (0)
; __device__ __forceinline__ void xcd_barrier(const XcdBarrier& b) {
;     ...
;         } else {
;             XB_SPIN(xb_ld(&bar[XB_XGEN(b.x)]) == gen, bar);
;             __builtin_amdgcn_fence(__ATOMIC_ACQUIRE, "agent");
;             asm volatile("s_waitcnt vmcnt(0)" ::: "memory");
.LBB0_689:
	v_readlane_b32 s4, v240, 6
	v_readlane_b32 s5, v240, 7
	s_add_i32 s3, s3, 1
	s_mov_b64 s[36:37], -1
	s_nop 2
	global_load_dword v2, v0, s[4:5] sc1
	s_waitcnt vmcnt(0)
	v_cmp_ne_u32_e32 vcc, v2, v1
	s_orn2_b64 s[34:35], vcc, exec
	s_branch .LBB0_684

; __device__ __forceinline__ unsigned xb_add(unsigned* p, unsigned v) { return __hip_atomic_fetch_add(p, v, __ATOMIC_RELAXED, __HIP_MEMORY_SCOPE_AGENT); }
; __device__ __forceinline__ void xcd_barrier(const XcdBarrier& b) {
;     ...
;             __builtin_amdgcn_fence(__ATOMIC_ACQUIRE, "agent");
;             xb_add(&bar[XB_XGEN(b.x)], 1u);
.LBB0_712:
	s_or_b64 exec, exec, s[22:23]
	s_mov_b64 s[22:23], exec
	v_mbcnt_lo_u32_b32 v0, s22, 0
	v_mbcnt_hi_u32_b32 v0, s23, v0
	v_cmp_eq_u32_e32 vcc, 0, v0
	s_waitcnt vmcnt(0)
	buffer_inv sc1
	s_and_saveexec_b64 s[26:27], vcc
	s_cbranch_execz .LBB0_714
	s_bcnt1_i32_b64 s3, s[22:23]
	v_readlane_b32 s4, v240, 2
	v_mov_b32_e32 v0, 0
	v_mov_b32_e32 v1, s3
	v_readlane_b32 s5, v240, 3
	s_nop 4
.LBB0_714:
	s_or_b64 exec, exec, s[26:27]
	s_waitcnt vmcnt(0)

; __device__ __forceinline__ unsigned xb_ld(unsigned* p)              { return __hip_atomic_load(p, __ATOMIC_RELAXED, __HIP_MEMORY_SCOPE_AGENT); }
; __device__ __forceinline__ unsigned xb_add(unsigned* p, unsigned v) { return __hip_atomic_fetch_add(p, v, __ATOMIC_RELAXED, __HIP_MEMORY_SCOPE_AGENT); }
; #define XB_SPIN(cond, bar) do { unsigned _sp = 0; while (cond) { __builtin_amdgcn_s_sleep(1); \
;     if ((++_sp & 255u) == 0u) { if (xb_ld(&(bar)[XB_TMO])) break; if (_sp > XB_SPIN_CAP) { atomicAdd(&(bar)[XB_TMO], 1u); break; } } } } while (0)
; __device__ __forceinline__ void xcd_barrier(const XcdBarrier& b) {
;     ...
;         const unsigned old = xb_add(&bar[XB_XSUB(b.x)], 1u);
;         const unsigned gen = old / nloc;
;         if (old + 1u == (gen + 1u) * nloc) {
;             __builtin_amdgcn_fence(__ATOMIC_RELEASE, "agent");
;             asm volatile("s_waitcnt vmcnt(0)" ::: "memory");
;             const unsigned og = xb_add(&bar[XB_TOP], 1u);
;             const unsigned tg = og / nx;
;             if (og + 1u == (tg + 1u) * nx) xb_add(&bar[XB_TOPGEN], 1u);
;             else XB_SPIN(xb_ld(&bar[XB_TOPGEN]) == tg, bar);
;             __builtin_amdgcn_fence(__ATOMIC_ACQUIRE, "agent");
;             xb_add(&bar[XB_XGEN(b.x)], 1u);
;             asm volatile("s_waitcnt vmcnt(0)" ::: "memory");
;         } else {
;             XB_SPIN(xb_ld(&bar[XB_XGEN(b.x)]) == gen, bar);
.LBB0_757:
	s_or_b64 exec, exec, s[22:23]
	v_cvt_f32_u32_e32 v4, v2
	s_waitcnt vmcnt(0)
	v_readfirstlane_b32 s3, v3
	v_sub_u32_e32 v3, 0, v2
	v_rcp_iflag_f32_e32 v4, v4
	v_add_u32_e32 v5, s3, v1
	v_mul_f32_e32 v4, 0x4f7ffffe, v4
	v_cvt_u32_f32_e32 v4, v4
	v_mul_lo_u32 v1, v3, v4
	v_mul_hi_u32 v1, v4, v1
	v_add_u32_e32 v1, v4, v1
	v_mul_hi_u32 v1, v5, v1
	v_mul_lo_u32 v3, v1, v2
	v_sub_u32_e32 v3, v5, v3
	v_add_u32_e32 v4, 1, v1
	v_cmp_ge_u32_e32 vcc, v3, v2
	s_nop 1
	v_cndmask_b32_e32 v1, v1, v4, vcc
	v_sub_u32_e32 v4, v3, v2
	v_cndmask_b32_e32 v3, v3, v4, vcc
	v_add_u32_e32 v4, 1, v1
	v_cmp_ge_u32_e32 vcc, v3, v2
	v_add_u32_e32 v3, 1, v5
	s_nop 0
	v_cndmask_b32_e32 v1, v1, v4, vcc
	v_mul_lo_u32 v4, v2, v1
	v_add_u32_e32 v2, v4, v2
	v_cmp_ne_u32_e32 vcc, v3, v2
	s_and_saveexec_b64 s[22:23], vcc
	s_xor_b64 s[22:23], exec, s[22:23]
	s_cbranch_execz .LBB0_771
	v_readlane_b32 s4, v240, 6
	s_waitcnt lgkmcnt(0)
	v_mov_b32_e32 v0, 0
	v_readlane_b32 s5, v240, 7
	s_nop 4
	global_load_dword v2, v0, s[4:5] sc1
	s_waitcnt vmcnt(0)
	v_cmp_eq_u32_e32 vcc, v2, v1
	s_and_saveexec_b64 s[26:27], vcc
	s_cbranch_execz .LBB0_770
	s_mov_b32 s3, 1
	s_mov_b64 s[30:31], 0
	s_branch .LBB0_761

; __device__ __forceinline__ unsigned xb_ld(unsigned* p)              { return __hip_atomic_load(p, __ATOMIC_RELAXED, __HIP_MEMORY_SCOPE_AGENT); }
; #define XB_SPIN(cond, bar) do { unsigned _sp = 0; while (cond) { __builtin_amdgcn_s_sleep(1); \
;     if ((++_sp & 255u) == 0u) { if (xb_ld(&(bar)[XB_TMO])) break; if (_sp > XB_SPIN_CAP) { atomicAdd(&(bar)[XB_TMO], 1u); break; } } } } while (0)
; __device__ __forceinline__ void xcd_barrier(const XcdBarrier& b) {
;     ...
;         } else {
;             XB_SPIN(xb_ld(&bar[XB_XGEN(b.x)]) == gen, bar);
;             __builtin_amdgcn_fence(__ATOMIC_ACQUIRE, "agent");
;             asm volatile("s_waitcnt vmcnt(0)" ::: "memory");
.LBB0_765:
	v_readlane_b32 s4, v240, 6
	v_readlane_b32 s5, v240, 7
	s_add_i32 s3, s3, 1
	s_mov_b64 s[38:39], -1
	s_nop 2
	global_load_dword v2, v0, s[4:5] sc1
	s_waitcnt vmcnt(0)
	v_cmp_ne_u32_e32 vcc, v2, v1
	s_orn2_b64 s[36:37], vcc, exec
	s_branch .LBB0_760

; __device__ __forceinline__ unsigned xb_add(unsigned* p, unsigned v) { return __hip_atomic_fetch_add(p, v, __ATOMIC_RELAXED, __HIP_MEMORY_SCOPE_AGENT); }
; __device__ __forceinline__ void xcd_barrier(const XcdBarrier& b) {
;     ...
;             __builtin_amdgcn_fence(__ATOMIC_ACQUIRE, "agent");
;             xb_add(&bar[XB_XGEN(b.x)], 1u);
.LBB0_788:
	s_or_b64 exec, exec, s[22:23]
	s_mov_b64 s[22:23], exec
	v_mbcnt_lo_u32_b32 v0, s22, 0
	v_mbcnt_hi_u32_b32 v0, s23, v0
	v_cmp_eq_u32_e32 vcc, 0, v0
	s_waitcnt vmcnt(0)
	buffer_inv sc1
	s_and_saveexec_b64 s[26:27], vcc
	s_cbranch_execz .LBB0_790
	s_bcnt1_i32_b64 s3, s[22:23]
	v_readlane_b32 s4, v240, 2
	v_mov_b32_e32 v0, 0
	v_mov_b32_e32 v1, s3
	v_readlane_b32 s5, v240, 3
	s_nop 4
.LBB0_790:
	s_or_b64 exec, exec, s[26:27]
	s_waitcnt vmcnt(0)

; __device__ __forceinline__ unsigned xb_add(unsigned* p, unsigned v) { return __hip_atomic_fetch_add(p, v, __ATOMIC_RELAXED, __HIP_MEMORY_SCOPE_AGENT); }
; __device__ __forceinline__ void xcd_barrier(const XcdBarrier& b) {
;     ...
;             __builtin_amdgcn_fence(__ATOMIC_ACQUIRE, "agent");
;             xb_add(&bar[XB_XGEN(b.x)], 1u);
.LBB0_853:
	s_or_b64 exec, exec, s[26:27]
	s_mov_b64 s[26:27], exec
	v_mbcnt_lo_u32_b32 v0, s26, 0
	v_mbcnt_hi_u32_b32 v0, s27, v0
	v_cmp_eq_u32_e32 vcc, 0, v0
	s_waitcnt vmcnt(0)
	buffer_inv sc1
	s_and_saveexec_b64 s[30:31], vcc
	s_cbranch_execz .LBB0_855
	s_bcnt1_i32_b64 s3, s[26:27]
	v_readlane_b32 s4, v240, 2
	v_mov_b32_e32 v0, 0
	v_mov_b32_e32 v1, s3
	v_readlane_b32 s5, v240, 3
	s_nop 4
.LBB0_855:
	s_or_b64 exec, exec, s[30:31]
	s_waitcnt vmcnt(0)

; __device__ __forceinline__ unsigned xb_ld(unsigned* p)              { return __hip_atomic_load(p, __ATOMIC_RELAXED, __HIP_MEMORY_SCOPE_AGENT); }
; __device__ __forceinline__ unsigned xb_add(unsigned* p, unsigned v) { return __hip_atomic_fetch_add(p, v, __ATOMIC_RELAXED, __HIP_MEMORY_SCOPE_AGENT); }
; #define XB_SPIN(cond, bar) do { unsigned _sp = 0; while (cond) { __builtin_amdgcn_s_sleep(1); \
;     if ((++_sp & 255u) == 0u) { if (xb_ld(&(bar)[XB_TMO])) break; if (_sp > XB_SPIN_CAP) { atomicAdd(&(bar)[XB_TMO], 1u); break; } } } } while (0)
; __device__ __forceinline__ void xcd_barrier(const XcdBarrier& b) {
;     ...
;         const unsigned old = xb_add(&bar[XB_XSUB(b.x)], 1u);
;         const unsigned gen = old / nloc;
;         if (old + 1u == (gen + 1u) * nloc) {
;             __builtin_amdgcn_fence(__ATOMIC_RELEASE, "agent");
;             asm volatile("s_waitcnt vmcnt(0)" ::: "memory");
;             const unsigned og = xb_add(&bar[XB_TOP], 1u);
;             const unsigned tg = og / nx;
;             if (og + 1u == (tg + 1u) * nx) xb_add(&bar[XB_TOPGEN], 1u);
;             else XB_SPIN(xb_ld(&bar[XB_TOPGEN]) == tg, bar);
;             __builtin_amdgcn_fence(__ATOMIC_ACQUIRE, "agent");
;             xb_add(&bar[XB_XGEN(b.x)], 1u);
;             asm volatile("s_waitcnt vmcnt(0)" ::: "memory");
;         } else {
;             XB_SPIN(xb_ld(&bar[XB_XGEN(b.x)]) == gen, bar);
.LBB0_891:
	s_or_b64 exec, exec, s[20:21]
	v_cvt_f32_u32_e32 v4, v2
	s_waitcnt vmcnt(0)
	v_readfirstlane_b32 s3, v3
	v_sub_u32_e32 v3, 0, v2
	v_rcp_iflag_f32_e32 v4, v4
	v_add_u32_e32 v5, s3, v1
	v_mul_f32_e32 v4, 0x4f7ffffe, v4
	v_cvt_u32_f32_e32 v4, v4
	v_mul_lo_u32 v1, v3, v4
	v_mul_hi_u32 v1, v4, v1
	v_add_u32_e32 v1, v4, v1
	v_mul_hi_u32 v1, v5, v1
	v_mul_lo_u32 v3, v1, v2
	v_sub_u32_e32 v3, v5, v3
	v_add_u32_e32 v4, 1, v1
	v_cmp_ge_u32_e32 vcc, v3, v2
	s_nop 1
	v_cndmask_b32_e32 v1, v1, v4, vcc
	v_sub_u32_e32 v4, v3, v2
	v_cndmask_b32_e32 v3, v3, v4, vcc
	v_add_u32_e32 v4, 1, v1
	v_cmp_ge_u32_e32 vcc, v3, v2
	v_add_u32_e32 v3, 1, v5
	s_nop 0
	v_cndmask_b32_e32 v1, v1, v4, vcc
	v_mul_lo_u32 v4, v2, v1
	v_add_u32_e32 v2, v4, v2
	v_cmp_ne_u32_e32 vcc, v3, v2
	s_and_saveexec_b64 s[20:21], vcc
	s_xor_b64 s[20:21], exec, s[20:21]
	s_cbranch_execz .LBB0_905
	v_readlane_b32 s4, v240, 6
	s_waitcnt lgkmcnt(0)
	v_mov_b32_e32 v0, 0
	v_readlane_b32 s5, v240, 7
	s_nop 4
	global_load_dword v2, v0, s[4:5] sc1
	s_waitcnt vmcnt(0)
	v_cmp_eq_u32_e32 vcc, v2, v1
	s_and_saveexec_b64 s[26:27], vcc
	s_cbranch_execz .LBB0_904
	s_mov_b32 s3, 1
	s_mov_b64 s[30:31], 0
	s_branch .LBB0_895

; __device__ __forceinline__ unsigned xb_add(unsigned* p, unsigned v) { return __hip_atomic_fetch_add(p, v, __ATOMIC_RELAXED, __HIP_MEMORY_SCOPE_AGENT); }
; __device__ __forceinline__ void xcd_barrier(const XcdBarrier& b) {
;     ...
;             __builtin_amdgcn_fence(__ATOMIC_ACQUIRE, "agent");
;             xb_add(&bar[XB_XGEN(b.x)], 1u);
.LBB0_922:
	s_or_b64 exec, exec, s[20:21]
	s_mov_b64 s[20:21], exec
	v_mbcnt_lo_u32_b32 v0, s20, 0
	v_mbcnt_hi_u32_b32 v0, s21, v0
	v_cmp_eq_u32_e32 vcc, 0, v0
	s_waitcnt vmcnt(0)
	buffer_inv sc1
	s_and_saveexec_b64 s[26:27], vcc
	s_cbranch_execz .LBB0_924
	s_bcnt1_i32_b64 s3, s[20:21]
	v_readlane_b32 s4, v240, 2
	v_mov_b32_e32 v0, 0
	v_mov_b32_e32 v1, s3
	v_readlane_b32 s5, v240, 3
	s_nop 4
.LBB0_924:
	s_or_b64 exec, exec, s[26:27]
	s_waitcnt vmcnt(0)

; __device__ __forceinline__ unsigned xb_ld(unsigned* p)              { return __hip_atomic_load(p, __ATOMIC_RELAXED, __HIP_MEMORY_SCOPE_AGENT); }
; __device__ __forceinline__ unsigned xb_add(unsigned* p, unsigned v) { return __hip_atomic_fetch_add(p, v, __ATOMIC_RELAXED, __HIP_MEMORY_SCOPE_AGENT); }
; #define XB_SPIN(cond, bar) do { unsigned _sp = 0; while (cond) { __builtin_amdgcn_s_sleep(1); \
;     if ((++_sp & 255u) == 0u) { if (xb_ld(&(bar)[XB_TMO])) break; if (_sp > XB_SPIN_CAP) { atomicAdd(&(bar)[XB_TMO], 1u); break; } } } } while (0)
; __device__ __forceinline__ void xcd_barrier(const XcdBarrier& b) {
;     ...
;         const unsigned old = xb_add(&bar[XB_XSUB(b.x)], 1u);
;         const unsigned gen = old / nloc;
;         if (old + 1u == (gen + 1u) * nloc) {
;             __builtin_amdgcn_fence(__ATOMIC_RELEASE, "agent");
;             asm volatile("s_waitcnt vmcnt(0)" ::: "memory");
;             const unsigned og = xb_add(&bar[XB_TOP], 1u);
;             const unsigned tg = og / nx;
;             if (og + 1u == (tg + 1u) * nx) xb_add(&bar[XB_TOPGEN], 1u);
;             else XB_SPIN(xb_ld(&bar[XB_TOPGEN]) == tg, bar);
;             __builtin_amdgcn_fence(__ATOMIC_ACQUIRE, "agent");
;             xb_add(&bar[XB_XGEN(b.x)], 1u);
;             asm volatile("s_waitcnt vmcnt(0)" ::: "memory");
;         } else {
;             XB_SPIN(xb_ld(&bar[XB_XGEN(b.x)]) == gen, bar);
.LBB0_971:
	s_or_b64 exec, exec, s[2:3]
	v_cvt_f32_u32_e32 v4, v2
	s_waitcnt vmcnt(0)
	v_readfirstlane_b32 s2, v3
	v_sub_u32_e32 v3, 0, v2
	v_rcp_iflag_f32_e32 v4, v4
	v_add_u32_e32 v5, s2, v1
	v_mul_f32_e32 v4, 0x4f7ffffe, v4
	v_cvt_u32_f32_e32 v4, v4
	v_mul_lo_u32 v1, v3, v4
	v_mul_hi_u32 v1, v4, v1
	v_add_u32_e32 v1, v4, v1
	v_mul_hi_u32 v1, v5, v1
	v_mul_lo_u32 v3, v1, v2
	v_sub_u32_e32 v3, v5, v3
	v_add_u32_e32 v4, 1, v1
	v_cmp_ge_u32_e32 vcc, v3, v2
	s_nop 1
	v_cndmask_b32_e32 v1, v1, v4, vcc
	v_sub_u32_e32 v4, v3, v2
	v_cndmask_b32_e32 v3, v3, v4, vcc
	v_add_u32_e32 v4, 1, v1
	v_cmp_ge_u32_e32 vcc, v3, v2
	v_add_u32_e32 v3, 1, v5
	s_nop 0
	v_cndmask_b32_e32 v1, v1, v4, vcc
	v_mul_lo_u32 v4, v2, v1
	v_add_u32_e32 v2, v4, v2
	v_cmp_ne_u32_e32 vcc, v3, v2
	s_and_saveexec_b64 s[2:3], vcc
	s_xor_b64 s[2:3], exec, s[2:3]
	s_cbranch_execz .LBB0_985
	v_readlane_b32 s4, v240, 6
	s_waitcnt lgkmcnt(0)
	v_mov_b32_e32 v0, 0
	v_readlane_b32 s5, v240, 7
	s_nop 4
	global_load_dword v2, v0, s[4:5] sc1
	s_waitcnt vmcnt(0)
	v_cmp_eq_u32_e32 vcc, v2, v1
	s_and_saveexec_b64 s[4:5], vcc
	s_cbranch_execz .LBB0_984
	s_mov_b32 s16, 1
	s_mov_b64 s[6:7], 0
	s_branch .LBB0_975

; __device__ __forceinline__ unsigned xb_ld(unsigned* p)              { return __hip_atomic_load(p, __ATOMIC_RELAXED, __HIP_MEMORY_SCOPE_AGENT); }
; #define XB_SPIN(cond, bar) do { unsigned _sp = 0; while (cond) { __builtin_amdgcn_s_sleep(1); \
;     if ((++_sp & 255u) == 0u) { if (xb_ld(&(bar)[XB_TMO])) break; if (_sp > XB_SPIN_CAP) { atomicAdd(&(bar)[XB_TMO], 1u); break; } } } } while (0)
; __device__ __forceinline__ void xcd_barrier(const XcdBarrier& b) {
;     ...
;         } else {
;             XB_SPIN(xb_ld(&bar[XB_XGEN(b.x)]) == gen, bar);
;             __builtin_amdgcn_fence(__ATOMIC_ACQUIRE, "agent");
;             asm volatile("s_waitcnt vmcnt(0)" ::: "memory");
.LBB0_979:
	v_readlane_b32 s10, v240, 6
	v_readlane_b32 s11, v240, 7
	s_add_i32 s16, s16, 1
	s_mov_b64 s[12:13], -1
	s_nop 2
	global_load_dword v2, v0, s[10:11] sc1
	s_waitcnt vmcnt(0)
	v_cmp_ne_u32_e32 vcc, v2, v1
	s_orn2_b64 s[10:11], vcc, exec
	s_branch .LBB0_974

; __device__ __forceinline__ unsigned xb_add(unsigned* p, unsigned v) { return __hip_atomic_fetch_add(p, v, __ATOMIC_RELAXED, __HIP_MEMORY_SCOPE_AGENT); }
; __device__ __forceinline__ void xcd_barrier(const XcdBarrier& b) {
;     ...
;             __builtin_amdgcn_fence(__ATOMIC_ACQUIRE, "agent");
;             xb_add(&bar[XB_XGEN(b.x)], 1u);
.LBB0_1002:
	s_or_b64 exec, exec, s[2:3]
	s_mov_b64 s[2:3], exec
	v_mbcnt_lo_u32_b32 v0, s2, 0
	v_mbcnt_hi_u32_b32 v0, s3, v0
	v_cmp_eq_u32_e32 vcc, 0, v0
	s_waitcnt vmcnt(0)
	buffer_inv sc1
	s_and_saveexec_b64 s[4:5], vcc
	s_cbranch_execz .LBB0_1004
	s_bcnt1_i32_b64 s2, s[2:3]
	v_mov_b32_e32 v1, s2
	v_readlane_b32 s2, v240, 2
	v_mov_b32_e32 v0, 0
	v_readlane_b32 s3, v240, 3
	s_nop 4
.LBB0_1004:
	s_or_b64 exec, exec, s[4:5]
	s_waitcnt vmcnt(0)
